# both scans (GDN + RWKV-7) inner loops on f32 MFMA 16x16x4, state in accumulator tiles, solve folded: Lak/Mqk/Mqb products as MFMAs
# speedup vs baseline: 1.0959x; 1.0679x over previous
.LBB0_563:
	s_or_b64 exec, exec, s[0:1]
	v_lshlrev_b64 v[2:3], 9, v[2:3]
	v_mov_b32_e32 v7, v94
	v_or_b32_e32 v2, v2, v1
	v_lshl_add_u64 v[4:5], v[4:5], 0, v[6:7]
	v_lshl_add_u64 v[8:9], v[2:3], 2, s[34:35]
	v_lshl_add_u64 v[6:7], v[2:3], 1, s[62:63]
	s_waitcnt vmcnt(4)
	v_lshl_add_u64 v[10:11], v[4:5], 0, s[76:77]
	global_load_dword v107, v[8:9], off
	global_load_ushort v18, v[4:5], off
	global_load_ushort v1, v[4:5], off offset:3072
	global_load_ushort v19, v[10:11], off offset:1024
	global_load_ushort v20, v[4:5], off offset:1024
	global_load_ushort v21, v[10:11], off offset:2048
	global_load_ushort v22, v[6:7], off
	global_load_ushort v23, v[4:5], off offset:2048
	v_or_b32_e32 v4, 0x200, v2
	v_mov_b32_e32 v5, v3
	v_lshl_add_u64 v[6:7], v[4:5], 1, s[62:63]
	v_lshl_add_u64 v[4:5], v[4:5], 2, s[34:35]
	v_or_b32_e32 v12, 0x400, v2
	v_mov_b32_e32 v13, v3
	v_lshl_add_u64 v[8:9], v[10:11], 0, s[76:77]
	s_waitcnt vmcnt(11)
	v_lshl_add_u64 v[14:15], v[12:13], 1, s[62:63]
	v_lshl_add_u64 v[12:13], v[12:13], 2, s[34:35]
	global_load_ushort v24, v[6:7], off
	global_load_dword v108, v[4:5], off
	global_load_ushort v25, v[8:9], off offset:3072
	global_load_ushort v26, v[8:9], off offset:1024
	global_load_ushort v27, v[14:15], off
	global_load_dword v109, v[12:13], off
	global_load_ushort v28, v[8:9], off offset:2048
	global_load_ushort v29, v[10:11], off offset:3072
	v_or_b32_e32 v4, 0x600, v2
	v_mov_b32_e32 v5, v3
	v_lshl_add_u64 v[16:17], v[8:9], 0, s[76:77]
	v_lshl_add_u64 v[6:7], v[4:5], 1, s[62:63]
	v_lshl_add_u64 v[4:5], v[4:5], 2, s[34:35]
	v_lshl_add_u64 v[8:9], v[16:17], 0, s[76:77]
	global_load_ushort v30, v[16:17], off offset:1024
	global_load_ushort v31, v[16:17], off offset:2048
	global_load_ushort v32, v[6:7], off
	global_load_dword v110, v[4:5], off
	global_load_ushort v33, v[8:9], off offset:3072
	global_load_ushort v36, v[8:9], off offset:1024
	global_load_ushort v37, v[8:9], off offset:2048
	s_nop 0
	global_load_ushort v16, v[16:17], off offset:3072
	v_or_b32_e32 v4, 0xa00, v2
	v_mov_b32_e32 v5, v3
	v_or_b32_e32 v10, 0x800, v2
	v_mov_b32_e32 v11, v3
	v_lshl_add_u64 v[14:15], v[8:9], 0, s[76:77]
	v_lshl_add_u64 v[6:7], v[4:5], 1, s[62:63]
	v_lshl_add_u64 v[4:5], v[4:5], 2, s[34:35]
	v_lshl_add_u64 v[12:13], v[10:11], 1, s[62:63]
	global_load_ushort v17, v[14:15], off offset:1024
	global_load_ushort v38, v[14:15], off offset:2048
	global_load_ushort v39, v[6:7], off
	global_load_dword v112, v[4:5], off
	global_load_ushort v40, v[14:15], off offset:3072
	global_load_ushort v41, v[12:13], off
	v_lshl_add_u64 v[4:5], v[14:15], 0, s[76:77]
	v_or_b32_e32 v6, 0xc00, v2
	v_mov_b32_e32 v7, v3
	v_lshl_add_u64 v[12:13], v[4:5], 0, s[76:77]
	v_or_b32_e32 v2, 0xe00, v2
	v_lshl_add_u64 v[8:9], v[6:7], 1, s[62:63]
	global_load_ushort v14, v[12:13], off offset:1024
	s_nop 0
	global_load_ushort v12, v[12:13], off offset:2048
	s_nop 0
	global_load_ushort v13, v[4:5], off offset:3072
	global_load_ushort v15, v[4:5], off offset:1024
	global_load_ushort v42, v[4:5], off offset:2048
	v_lshl_add_u64 v[4:5], v[2:3], 1, s[62:63]
	global_load_ushort v43, v[4:5], off
	s_nop 0
	global_load_ushort v8, v[8:9], off
	v_lshl_add_u64 v[4:5], v[6:7], 2, s[34:35]
	v_lshl_add_u64 v[2:3], v[2:3], 2, s[34:35]
	v_lshl_add_u64 v[10:11], v[10:11], 2, s[34:35]
	global_load_dword v113, v[4:5], off
	global_load_dword v114, v[2:3], off
	global_load_dword v111, v[10:11], off
	s_waitcnt vmcnt(38)
	v_lshlrev_b32_e32 v44, 16, v18
	s_waitcnt vmcnt(37)
	v_lshlrev_b32_e32 v1, 16, v1
	s_waitcnt vmcnt(36)
	v_lshlrev_b32_e32 v45, 16, v19
	s_waitcnt vmcnt(35)
	v_lshlrev_b32_e32 v46, 16, v20
	s_waitcnt vmcnt(34)
	v_lshlrev_b32_e32 v47, 16, v21
	s_waitcnt vmcnt(33)
	v_lshlrev_b32_e32 v50, 16, v22
	s_waitcnt vmcnt(32)
	v_lshlrev_b32_e32 v48, 16, v23
	s_waitcnt vmcnt(31)
	v_lshlrev_b32_e32 v51, 16, v24
	s_waitcnt vmcnt(29)
	v_lshlrev_b32_e32 v49, 16, v25
	s_waitcnt vmcnt(28)
	v_lshlrev_b32_e32 v54, 16, v26
	s_waitcnt vmcnt(27)
	v_lshlrev_b32_e32 v58, 16, v27
	s_waitcnt vmcnt(25)
	v_lshlrev_b32_e32 v56, 16, v28
	s_waitcnt vmcnt(24)
	v_lshlrev_b32_e32 v52, 16, v29
	s_waitcnt vmcnt(23)
	v_lshlrev_b32_e32 v53, 16, v30
	s_waitcnt vmcnt(22)
	v_lshlrev_b32_e32 v55, 16, v31
	s_waitcnt vmcnt(21)
	v_lshlrev_b32_e32 v57, 16, v32
	s_waitcnt vmcnt(19)
	v_lshlrev_b32_e32 v59, 16, v33
	s_waitcnt vmcnt(18)
	v_lshlrev_b32_e32 v62, 16, v36
	s_waitcnt vmcnt(17)
	v_lshlrev_b32_e32 v64, 16, v37
	s_waitcnt vmcnt(16)
	v_lshlrev_b32_e32 v60, 16, v16
	v_mov_b64_e32 v[36:37], v[94:95]
	s_waitcnt vmcnt(15)
	v_lshlrev_b32_e32 v61, 16, v17
	s_waitcnt vmcnt(14)
	v_lshlrev_b32_e32 v63, 16, v38
	s_waitcnt vmcnt(13)
	v_lshlrev_b32_e32 v65, 16, v39
	v_mov_b64_e32 v[38:39], v[94:95]
	s_waitcnt vmcnt(11)
	v_lshlrev_b32_e32 v67, 16, v40
	s_waitcnt vmcnt(10)
	v_lshlrev_b32_e32 v66, 16, v41
	v_mov_b64_e32 v[40:41], v[94:95]
	s_waitcnt vmcnt(9)
	v_lshlrev_b32_e32 v70, 16, v14
	s_waitcnt vmcnt(8)
	v_lshlrev_b32_e32 v72, 16, v12
	s_waitcnt vmcnt(7)
	v_lshlrev_b32_e32 v68, 16, v13
	s_waitcnt vmcnt(6)
	v_lshlrev_b32_e32 v69, 16, v15
	s_waitcnt vmcnt(5)
	v_lshlrev_b32_e32 v71, 16, v42
	s_waitcnt vmcnt(4)
	v_lshlrev_b32_e32 v73, 16, v43
	s_waitcnt vmcnt(3)
	v_lshlrev_b32_e32 v74, 16, v8
	v_mov_b64_e32 v[42:43], v[94:95]
	v_mov_b32_e32 v224, 0
	v_mov_b32_e32 v225, 0
	v_mov_b32_e32 v226, 0
	v_mov_b32_e32 v227, 0
	v_mov_b32_e32 v228, 0
	v_mov_b32_e32 v229, 0
	v_mov_b32_e32 v230, 0
	v_mov_b32_e32 v231, 0
	v_mov_b32_e32 v232, 0
	v_mov_b32_e32 v233, 0
	v_mov_b32_e32 v234, 0
	v_mov_b32_e32 v235, 0
	v_mov_b32_e32 v236, 0
	v_mov_b32_e32 v237, 0
	v_mov_b32_e32 v238, 0
	v_mov_b32_e32 v239, 0

.LBB0_586:
.Lrw_entry:
	v_readfirstlane_b32 s0, v180
	s_nop 1
	s_cmpk_ge_u32 s0, 0x100
	s_cbranch_scc1 .Lrw_done
	v_and_b32_e32 v222, 15, v180
	v_bfe_u32 v223, v180, 4, 2
	v_lshrrev_b32_e32 v240, 6, v180
	v_and_b32_e32 v176, 7, v222
	v_mul_u32_u24_e32 v176, 0x110, v176
	v_and_b32_e32 v177, 8, v222
	v_mul_u32_u24_e32 v177, 0x880, v177
	v_lshl_add_u32 v168, v223, 4, v176
	v_add_u32_e32 v168, v168, v177
	v_lshlrev_b32_e32 v178, 6, v240
	v_lshl_add_u32 v178, v222, 2, v178
	v_lshl_add_u32 v169, v223, 8, v178
	v_add_u32_e32 v169, s41, v169
	v_lshl_add_u32 v175, v223, 10, v178
	v_add_u32_e32 v175, 0x1f000, v175
	v_mov_b32_e32 v170, 0x15800
	v_lshlrev_b32_e32 v176, 5, v222
	v_lshl_add_u32 v176, v223, 2, v176
	v_and_b32_e32 v177, 8, v222
	v_lshl_add_u32 v172, v177, 5, v176
	v_add_u32_e32 v171, 0x15900, v172
	v_add_u32_e32 v172, 0x15800, v172
	v_mul_u32_u24_e32 v176, 0x110, v223
	v_lshl_add_u32 v173, v222, 2, v176
	v_add_u32_e32 v173, 0x8800, v173
	v_lshlrev_b32_e32 v174, 4, v223
	v_add_u32_e32 v174, 0x11000, v174
	v_cmp_eq_u32_e32 vcc, 1, v223
	v_cmp_eq_u32_e64 s[4:5], 2, v223
	v_cmp_eq_u32_e64 s[6:7], 3, v223
	s_mov_b32 s8, 0
	s_mov_b32 s9, -1
	v_mov_b32_e32 v198, 1.0
	v_mov_b32_e32 v199, 1.0
	v_mov_b32_e32 v200, 1.0
	v_mov_b32_e32 v201, 1.0
	v_mov_b32_e32 v202, 1.0
	v_mov_b32_e32 v203, 1.0
	v_mov_b32_e32 v204, 1.0
	v_mov_b32_e32 v205, 1.0
	v_mov_b32_e32 v206, 1.0
	v_mov_b32_e32 v207, 1.0
	v_mov_b32_e32 v208, 1.0
	v_mov_b32_e32 v209, 1.0
	v_mov_b32_e32 v210, 1.0
	v_mov_b32_e32 v211, 1.0
	v_mov_b32_e32 v212, 1.0
	v_mov_b32_e32 v213, 1.0
	ds_read_b128 v[2:5], v168 offset:0
	ds_read_b128 v[6:9], v168 offset:64
	ds_read_b128 v[10:13], v168 offset:128
	ds_read_b128 v[14:17], v168 offset:192
	ds_read_b32 v216, v171 offset:0
	ds_read_b32 v217, v171 offset:16
	ds_read_b32 v214, v169 offset:0
	ds_read_b32 v215, v169 offset:1024
	ds_read_b128 v[124:127], v170 offset:32
	ds_read_b128 v[128:131], v170 offset:64
	ds_read_b128 v[132:135], v170 offset:96
	ds_read_b128 v[136:139], v170 offset:128
	ds_read_b128 v[140:143], v170 offset:144
	ds_read_b128 v[144:147], v170 offset:160
	ds_read_b128 v[148:151], v170 offset:176
	ds_read_b128 v[152:155], v170 offset:192
	ds_read_b128 v[156:159], v170 offset:208
	ds_read_b128 v[160:163], v170 offset:224
	ds_read_b128 v[164:167], v170 offset:240
	ds_read_b32 v218, v172 offset:0
	ds_read_b32 v219, v172 offset:16
	ds_read_b32 v182, v173 offset:0
	ds_read_b32 v183, v173 offset:1088
	ds_read_b32 v184, v173 offset:17408
	ds_read_b32 v185, v173 offset:18496
	ds_read_b32 v186, v173 offset:64
	ds_read_b32 v187, v173 offset:1152
	ds_read_b32 v188, v173 offset:17472
	ds_read_b32 v189, v173 offset:18560
	ds_read_b32 v190, v173 offset:128
	ds_read_b32 v191, v173 offset:1216
	ds_read_b32 v192, v173 offset:17536
	ds_read_b32 v193, v173 offset:18624
	ds_read_b32 v194, v173 offset:192
	ds_read_b32 v195, v173 offset:1280
	ds_read_b32 v196, v173 offset:17600
	ds_read_b32 v197, v173 offset:18688
	s_mov_b32 s1, 0
.Lrw_loop:
	s_waitcnt lgkmcnt(0)
	v_pk_mul_f32 v[224:225], v[224:225], v[198:199]
	v_pk_mul_f32 v[226:227], v[226:227], v[200:201]
	v_pk_mul_f32 v[228:229], v[228:229], v[202:203]
	v_pk_mul_f32 v[230:231], v[230:231], v[204:205]
	v_mfma_f32_16x16x4_f32 v[18:21], v2, v224, 0
	v_mfma_f32_16x16x4_f32 v[22:25], v3, v225, 0
	v_mfma_f32_16x16x4_f32 v[18:21], v4, v226, v[18:21]
	v_mfma_f32_16x16x4_f32 v[22:25], v5, v227, v[22:25]
	v_pk_mul_f32 v[232:233], v[232:233], v[206:207]
	v_pk_mul_f32 v[234:235], v[234:235], v[208:209]
	v_mfma_f32_16x16x4_f32 v[18:21], v6, v228, v[18:21]
	v_mfma_f32_16x16x4_f32 v[22:25], v7, v229, v[22:25]
	v_mfma_f32_16x16x4_f32 v[18:21], v8, v230, v[18:21]
	v_mfma_f32_16x16x4_f32 v[22:25], v9, v231, v[22:25]
	v_pk_mul_f32 v[236:237], v[236:237], v[210:211]
	v_pk_mul_f32 v[238:239], v[238:239], v[212:213]
	v_mfma_f32_16x16x4_f32 v[18:21], v10, v232, v[18:21]
	v_mfma_f32_16x16x4_f32 v[22:25], v11, v233, v[22:25]
	v_mfma_f32_16x16x4_f32 v[18:21], v12, v234, v[18:21]
	v_mfma_f32_16x16x4_f32 v[22:25], v13, v235, v[22:25]
	v_mfma_f32_16x16x4_f32 v[18:21], v14, v236, v[18:21]
	v_mfma_f32_16x16x4_f32 v[22:25], v15, v237, v[22:25]
	v_mfma_f32_16x16x4_f32 v[18:21], v16, v238, v[18:21]
	v_mfma_f32_16x16x4_f32 v[22:25], v17, v239, v[22:25]
	v_mfma_f32_16x16x4_f32 v[18:21], v216, v214, v[18:21]
	v_mfma_f32_16x16x4_f32 v[22:25], v217, v215, v[22:25]
	ds_read_b128 v[2:5], v168 offset:2176
	ds_read_b128 v[6:9], v168 offset:2240
	ds_read_b128 v[10:13], v168 offset:2304
	ds_read_b128 v[14:17], v168 offset:2368
	ds_read_b32 v216, v171 offset:1024
	ds_read_b32 v217, v171 offset:1040
	ds_read_b128 v[198:201], v174 offset:0
	ds_read_b128 v[202:205], v174 offset:64
	ds_read_b128 v[206:209], v174 offset:128
	ds_read_b128 v[210:213], v174 offset:192
	v_mfma_f32_16x16x4_f32 v[224:227], v184, v214, v[224:227]
	v_mfma_f32_16x16x4_f32 v[224:227], v185, v215, v[224:227]
	v_mfma_f32_16x16x4_f32 v[228:231], v188, v214, v[228:231]
	v_mfma_f32_16x16x4_f32 v[228:231], v189, v215, v[228:231]
	v_mfma_f32_16x16x4_f32 v[232:235], v192, v214, v[232:235]
	v_mfma_f32_16x16x4_f32 v[232:235], v193, v215, v[232:235]
	v_mfma_f32_16x16x4_f32 v[236:239], v196, v214, v[236:239]
	v_mfma_f32_16x16x4_f32 v[236:239], v197, v215, v[236:239]
	ds_read_b32 v214, v169 offset:2048
	ds_read_b32 v215, v169 offset:3072
	v_pk_add_f32 v[18:19], v[18:19], v[22:23]
	v_pk_add_f32 v[20:21], v[20:21], v[24:25]
	v_mov_b32_e32 v26, v18
	v_mov_b32_e32 v27, v19
	v_mov_b32_e32 v28, v20
	v_mov_b32_e32 v29, v21
	v_mov_b32_e32 v30, v18
	v_mov_b32_e32 v31, v19
	v_mov_b32_e32 v32, v20
	v_mov_b32_e32 v33, v21
	v_permlane32_swap_b32_e32 v26, v30
	v_permlane32_swap_b32_e32 v27, v31
	v_permlane32_swap_b32_e32 v28, v32
	v_permlane32_swap_b32_e32 v29, v33
	v_mov_b32_e32 v36, v26
	v_mov_b32_e32 v37, v27
	v_mov_b32_e32 v38, v28
	v_mov_b32_e32 v39, v29
	s_nop 0
	v_permlane16_swap_b32_e32 v26, v36
	v_permlane16_swap_b32_e32 v27, v37
	v_permlane16_swap_b32_e32 v28, v38
	v_permlane16_swap_b32_e32 v29, v39
	v_fmac_f32_e32 v27, v124, v26
	v_fmac_f32_e32 v28, v128, v26
	v_fmac_f32_e32 v29, v132, v26
	v_fmac_f32_e32 v36, v136, v26
	v_fmac_f32_e32 v37, v144, v26
	v_fmac_f32_e32 v38, v152, v26
	v_fmac_f32_e32 v39, v160, v26
	v_fmac_f32_e32 v28, v129, v27
	v_fmac_f32_e32 v29, v133, v27
	v_fmac_f32_e32 v36, v137, v27
	v_fmac_f32_e32 v37, v145, v27
	v_fmac_f32_e32 v38, v153, v27
	v_fmac_f32_e32 v39, v161, v27
	v_fmac_f32_e32 v29, v134, v28
	v_fmac_f32_e32 v36, v138, v28
	v_fmac_f32_e32 v37, v146, v28
	v_fmac_f32_e32 v38, v154, v28
	v_fmac_f32_e32 v39, v162, v28
	v_fmac_f32_e32 v36, v139, v29
	v_fmac_f32_e32 v37, v147, v29
	v_fmac_f32_e32 v38, v155, v29
	v_fmac_f32_e32 v39, v163, v29
	v_fmac_f32_e32 v37, v148, v36
	v_fmac_f32_e32 v38, v156, v36
	v_fmac_f32_e32 v39, v164, v36
	v_fmac_f32_e32 v38, v157, v37
	v_fmac_f32_e32 v39, v165, v37
	v_fmac_f32_e32 v39, v166, v38
	ds_read_b128 v[124:127], v170 offset:1056
	ds_read_b128 v[128:131], v170 offset:1088
	ds_read_b128 v[132:135], v170 offset:1120
	ds_read_b128 v[136:139], v170 offset:1152
	ds_read_b128 v[140:143], v170 offset:1168
	ds_read_b128 v[144:147], v170 offset:1184
	ds_read_b128 v[148:151], v170 offset:1200
	ds_read_b128 v[152:155], v170 offset:1216
	ds_read_b128 v[156:159], v170 offset:1232
	ds_read_b128 v[160:163], v170 offset:1248
	ds_read_b128 v[164:167], v170 offset:1264
	v_cndmask_b32_e32 v220, v26, v27, vcc
	v_cndmask_b32_e64 v220, v220, v28, s[4:5]
	v_cndmask_b32_e64 v220, v220, v29, s[6:7]
	v_cndmask_b32_e32 v221, v36, v37, vcc
	v_cndmask_b32_e64 v221, v221, v38, s[4:5]
	v_cndmask_b32_e64 v221, v221, v39, s[6:7]
	s_nop 1
	v_mfma_f32_16x16x4_f32 v[40:43], v218, v220, v[18:21]
	v_mfma_f32_16x16x4_f32 v[40:43], v219, v221, v[40:43]
	ds_read_b32 v218, v172 offset:1024
	ds_read_b32 v219, v172 offset:1040
	v_mfma_f32_16x16x4_f32 v[224:227], v182, v220, v[224:227]
	v_mfma_f32_16x16x4_f32 v[224:227], v183, v221, v[224:227]
	v_mfma_f32_16x16x4_f32 v[228:231], v186, v220, v[228:231]
	v_mfma_f32_16x16x4_f32 v[228:231], v187, v221, v[228:231]
	v_mfma_f32_16x16x4_f32 v[232:235], v190, v220, v[232:235]
	v_mfma_f32_16x16x4_f32 v[232:235], v191, v221, v[232:235]
	v_mfma_f32_16x16x4_f32 v[236:239], v194, v220, v[236:239]
	v_mfma_f32_16x16x4_f32 v[236:239], v195, v221, v[236:239]
	ds_read_b32 v182, v173 offset:2176
	ds_read_b32 v183, v173 offset:3264
	ds_read_b32 v184, v173 offset:19584
	ds_read_b32 v185, v173 offset:20672
	ds_read_b32 v186, v173 offset:2240
	ds_read_b32 v187, v173 offset:3328
	ds_read_b32 v188, v173 offset:19648
	ds_read_b32 v189, v173 offset:20736
	ds_read_b32 v190, v173 offset:2304
	ds_read_b32 v191, v173 offset:3392
	ds_read_b32 v192, v173 offset:19712
	ds_read_b32 v193, v173 offset:20800
	ds_read_b32 v194, v173 offset:2368
	ds_read_b32 v195, v173 offset:3456
	ds_read_b32 v196, v173 offset:19776
	ds_read_b32 v197, v173 offset:20864
	s_mov_b64 exec, s[8:9]
	ds_write_b32 v175, v40 offset:0
	ds_write_b32 v175, v41 offset:256
	ds_write_b32 v175, v42 offset:512
	ds_write_b32 v175, v43 offset:768
	s_mov_b64 exec, -1
	v_add_u32_e32 v168, 0x880, v168
	v_add_u32_e32 v169, 0x800, v169
	v_add_u32_e32 v170, 0x400, v170
	v_add_u32_e32 v171, 0x400, v171
	v_add_u32_e32 v172, 0x400, v172
	v_add_u32_e32 v173, 0x880, v173
	v_add_u32_e32 v174, 0x100, v174
	v_add_u32_e32 v175, 0x800, v175
	s_add_i32 s1, s1, 1
	s_cmp_lg_u32 s1, 8
	s_cbranch_scc1 .Lrw_loop
	s_waitcnt lgkmcnt(0)
	s_nop 7
	v_pk_mul_f32 v[224:225], v[224:225], v[198:199]
	v_pk_mul_f32 v[226:227], v[226:227], v[200:201]
	v_pk_mul_f32 v[228:229], v[228:229], v[202:203]
	v_pk_mul_f32 v[230:231], v[230:231], v[204:205]
	v_pk_mul_f32 v[232:233], v[232:233], v[206:207]
	v_pk_mul_f32 v[234:235], v[234:235], v[208:209]
	v_pk_mul_f32 v[236:237], v[236:237], v[210:211]
	v_pk_mul_f32 v[238:239], v[238:239], v[212:213]
.Lrw_done:
	s_add_i32 s40, s40, 1
	s_barrier
	s_add_u32 s0, s80, s17
	v_add_u32_e32 v2, s72, v76
	v_ashrrev_i32_e32 v3, 31, v2
	s_addc_u32 s1, s81, 0
	v_ashrrev_i32_e32 v79, 31, v78
	v_lshl_add_u64 v[4:5], s[0:1], 0, v[78:79]
	v_lshlrev_b64 v[8:9], 1, v[2:3]
	v_lshl_add_u64 v[10:11], s[50:51], 0, v[8:9]
	v_lshlrev_b64 v[6:7], 10, v[4:5]
	v_lshl_add_u64 v[4:5], v[10:11], 0, v[6:7]
	s_movk_i32 s3, 0x2000
	v_add_co_u32_e32 v10, vcc, s3, v4
	s_movk_i32 s3, 0x4000
	s_nop 0
	v_addc_co_u32_e32 v11, vcc, 0, v5, vcc
	v_add_co_u32_e32 v12, vcc, s3, v4
	s_movk_i32 s3, 0x6000
	s_nop 0
	v_addc_co_u32_e32 v13, vcc, 0, v5, vcc
	v_add_co_u32_e32 v14, vcc, s3, v4
	s_mov_b32 s3, 0x8000
	s_nop 0
	v_addc_co_u32_e32 v15, vcc, 0, v5, vcc
	v_add_co_u32_e32 v16, vcc, s3, v4
	s_mov_b32 s3, 0xa000
	s_nop 0
	v_addc_co_u32_e32 v17, vcc, 0, v5, vcc
	v_add_co_u32_e32 v18, vcc, s3, v4
	s_mov_b32 s3, 0xc000
	s_nop 0
	v_addc_co_u32_e32 v19, vcc, 0, v5, vcc
	v_add_co_u32_e32 v20, vcc, s3, v4
	s_mov_b32 s3, 0xe000
	s_nop 0
	v_addc_co_u32_e32 v21, vcc, 0, v5, vcc
	v_add_co_u32_e32 v22, vcc, s3, v4
	v_lshlrev_b64 v[2:3], 2, v[2:3]
	s_nop 0
	v_addc_co_u32_e32 v23, vcc, 0, v5, vcc
	global_load_ushort v24, v[4:5], off
	global_load_ushort v25, v[10:11], off
	s_nop 0
	global_load_ushort v12, v[12:13], off
	s_nop 0
	global_load_ushort v13, v[14:15], off
	s_nop 0
	global_load_ushort v14, v[16:17], off
	s_nop 0
	global_load_ushort v16, v[18:19], off
	global_load_ushort v17, v[20:21], off
	s_nop 0
	global_load_ushort v18, v[22:23], off
	v_lshlrev_b32_e32 v4, 6, v78
	v_add_lshl_u32 v19, v4, v76, 2
	v_add_u32_e32 v10, s96, v19
	v_lshl_add_u64 v[4:5], s[58:59], 0, v[2:3]
	ds_read_b32 v26, v10
	v_lshl_add_u64 v[10:11], s[60:61], 0, v[2:3]
	v_lshl_add_u64 v[2:3], s[24:25], 0, v[8:9]
	global_load_dword v9, v[4:5], off
	global_load_dword v8, v[10:11], off
	v_add_u32_e32 v19, s41, v19
	s_waitcnt lgkmcnt(0)
	v_add_f32_dpp v4, v26, v26 quad_perm:[1,0,3,2] row_mask:0xf bank_mask:0xf bound_ctrl:1
	ds_read_b32 v30, v19
	v_lshl_add_u64 v[6:7], v[2:3], 0, v[6:7]
	v_add_f32_dpp v4, v4, v4 quad_perm:[2,3,0,1] row_mask:0xf bank_mask:0xf bound_ctrl:1
	s_cmp_eq_u32 s40, 32
	s_waitcnt vmcnt(9)
	v_lshlrev_b32_e32 v24, 16, v24
	v_add_f32_dpp v4, v4, v4 row_half_mirror row_mask:0xf bank_mask:0xf bound_ctrl:1
	s_waitcnt vmcnt(7)
	v_lshlrev_b32_e32 v27, 16, v12
	v_lshl_add_u32 v12, v78, 2, s16
	v_add_f32_dpp v4, v4, v4 row_mirror row_mask:0xf bank_mask:0xf bound_ctrl:1
	s_waitcnt vmcnt(6)
	v_lshlrev_b32_e32 v15, 16, v13
	v_readlane_b32 s3, v4, 16
	s_waitcnt vmcnt(2)
	v_lshlrev_b32_e32 v10, 16, v18
	v_mul_f32_e32 v18, 0xbfb8aa3b, v24
	v_exp_f32_e32 v20, v18
	v_add_u32_e32 v18, 8, v78
	v_readlane_b32 s6, v4, 48
	v_lshlrev_b32_e32 v21, 6, v18
	v_readlane_b32 s4, v4, 0
	v_readlane_b32 s5, v4, 32
	v_mov_b32_e32 v4, s3
	v_mov_b32_e32 v5, s6
	v_add_lshl_u32 v28, v21, v76, 2
	v_pk_add_f32 v[4:5], s[4:5], v[4:5]
	v_add_u32_e32 v21, s96, v28
	v_add_f32_e32 v4, v4, v5
	ds_read_b32 v29, v21
	v_fmac_f32_e32 v26, 0xbc800000, v4
	v_mul_f32_e32 v4, v26, v26
	v_add_f32_e32 v19, 1.0, v20
	v_rcp_f32_e32 v31, v19
	v_mov_b32_dpp v4, v4 quad_perm:[1,0,3,2] row_mask:0xf bank_mask:0xf bound_ctrl:1
	v_fmac_f32_e32 v4, v26, v26
	s_waitcnt lgkmcnt(0)
	v_add_f32_dpp v19, v29, v29 quad_perm:[1,0,3,2] row_mask:0xf bank_mask:0xf bound_ctrl:1
	v_lshlrev_b32_e32 v13, 16, v16
	v_add_f32_dpp v4, v4, v4 quad_perm:[2,3,0,1] row_mask:0xf bank_mask:0xf bound_ctrl:1
	v_add_f32_dpp v19, v19, v19 quad_perm:[2,3,0,1] row_mask:0xf bank_mask:0xf bound_ctrl:1
	v_lshlrev_b32_e32 v11, 16, v17
	v_add_f32_dpp v4, v4, v4 row_half_mirror row_mask:0xf bank_mask:0xf bound_ctrl:1
	v_add_f32_dpp v19, v19, v19 row_half_mirror row_mask:0xf bank_mask:0xf bound_ctrl:1
	ds_read2_b32 v[16:17], v12 offset1:8
	v_add_f32_dpp v4, v4, v4 row_mirror row_mask:0xf bank_mask:0xf bound_ctrl:1
	v_add_f32_dpp v19, v19, v19 row_mirror row_mask:0xf bank_mask:0xf bound_ctrl:1
	v_readlane_b32 s3, v4, 16
	v_readlane_b32 s6, v4, 48
	v_readlane_b32 s4, v4, 0
	v_readlane_b32 s5, v4, 32
	v_mov_b32_e32 v4, s3
	v_mov_b32_e32 v5, s6
	v_readlane_b32 s3, v19, 16
	v_readlane_b32 s6, v19, 48
	v_pk_add_f32 v[4:5], s[4:5], v[4:5]
	v_readlane_b32 s4, v19, 0
	v_readlane_b32 s5, v19, 32
	v_mov_b32_e32 v20, s3
	v_mov_b32_e32 v21, s6
	v_pk_add_f32 v[20:21], s[4:5], v[20:21]
	v_mov_b32_e32 v23, v4
	v_add_f32_e32 v19, v20, v21
	v_fmac_f32_e32 v29, 0xbc800000, v19
	v_mul_f32_e32 v19, v29, v29
	v_lshlrev_b32_e32 v25, 16, v25
	v_lshlrev_b32_e32 v14, 16, v14
	v_mov_b32_dpp v19, v19 quad_perm:[1,0,3,2] row_mask:0xf bank_mask:0xf bound_ctrl:1
	v_fmac_f32_e32 v19, v29, v29
	s_nop 1
	v_add_f32_dpp v19, v19, v19 quad_perm:[2,3,0,1] row_mask:0xf bank_mask:0xf bound_ctrl:1
	s_nop 1
	v_add_f32_dpp v19, v19, v19 row_half_mirror row_mask:0xf bank_mask:0xf bound_ctrl:1
	s_nop 1
	v_add_f32_dpp v19, v19, v19 row_mirror row_mask:0xf bank_mask:0xf bound_ctrl:1
	s_nop 0
	v_readlane_b32 s3, v19, 16
	v_readlane_b32 s6, v19, 48
	v_readlane_b32 s4, v19, 0
	v_readlane_b32 s5, v19, 32
	v_mov_b32_e32 v20, s3
	v_mov_b32_e32 v21, s6
	v_pk_add_f32 v[20:21], s[4:5], v[20:21]
	s_mov_b32 s4, 0x3a27c5ac
	v_mov_b32_e32 v22, v20
	v_mov_b32_e32 v4, v21
	v_pk_add_f32 v[20:21], v[22:23], v[4:5]
	v_mov_b64_e32 v[4:5], s[4:5]
	v_pk_fma_f32 v[20:21], v[20:21], s[78:79], v[4:5] op_sel_hi:[1,0,0]
	s_nop 0
	v_mul_f32_e32 v19, 0x4b800000, v21
	v_cmp_gt_f32_e32 vcc, s91, v21
	s_nop 1
	v_cndmask_b32_e32 v19, v21, v19, vcc
	v_rsq_f32_e32 v21, v19
	v_ashrrev_i32_e32 v19, 31, v18
	v_lshl_add_u64 v[18:19], s[0:1], 0, v[18:19]
	v_mul_f32_e32 v22, 0x45800000, v21
	v_cndmask_b32_e32 v21, v21, v22, vcc
	v_mul_f32_e32 v21, v26, v21
	s_waitcnt vmcnt(0)
	v_fma_f32 v21, v9, v21, v8
	s_waitcnt lgkmcnt(0)
	v_fmac_f32_e32 v21, v16, v30
	v_mul_f32_e32 v16, v21, v24
	v_mul_f32_e32 v16, v31, v16
	v_mul_f32_e32 v21, 0x4b800000, v20
	v_cmp_gt_f32_e32 vcc, s91, v20
	s_nop 1
	v_cndmask_b32_e32 v20, v20, v21, vcc
	v_bfe_u32 v21, v16, 16, 1
	v_add3_u32 v16, v16, v21, s97
	v_rsq_f32_e32 v20, v20
	global_store_short_d16_hi v[6:7], v16, off
	v_mul_f32_e32 v7, 0xbfb8aa3b, v25
	v_exp_f32_e32 v7, v7
	v_add_u32_e32 v16, s41, v28
	ds_read_b32 v16, v16
	v_mul_f32_e32 v6, 0x45800000, v20
	v_cndmask_b32_e32 v6, v20, v6, vcc
	v_add_f32_e32 v7, 1.0, v7
	v_mul_f32_e32 v6, v29, v6
	v_rcp_f32_e32 v7, v7
	v_fma_f32 v6, v9, v6, v8
	s_waitcnt lgkmcnt(0)
	v_fmac_f32_e32 v6, v17, v16
	v_mul_f32_e32 v6, v6, v25
	v_mul_f32_e32 v6, v7, v6
	v_bfe_u32 v7, v6, 16, 1
	v_add_u32_e32 v16, 16, v78
	v_add3_u32 v17, v6, v7, s97
	v_lshlrev_b64 v[6:7], 10, v[18:19]
	v_lshlrev_b32_e32 v18, 6, v16
	v_add_lshl_u32 v20, v18, v76, 2
	v_add_u32_e32 v18, s96, v20
	ds_read_b32 v26, v18
	v_lshl_add_u64 v[6:7], v[2:3], 0, v[6:7]
	global_store_short_d16_hi v[6:7], v17, off
	v_ashrrev_i32_e32 v17, 31, v16
	v_lshl_add_u64 v[6:7], s[0:1], 0, v[16:17]
	s_waitcnt lgkmcnt(0)
	v_add_f32_dpp v16, v26, v26 quad_perm:[1,0,3,2] row_mask:0xf bank_mask:0xf bound_ctrl:1
	v_add_u32_e32 v21, s41, v20
	v_mul_f32_e32 v20, 0xbfb8aa3b, v27
	v_add_f32_dpp v16, v16, v16 quad_perm:[2,3,0,1] row_mask:0xf bank_mask:0xf bound_ctrl:1
	v_exp_f32_e32 v22, v20
	v_add_u32_e32 v20, 24, v78
	v_add_f32_dpp v16, v16, v16 row_half_mirror row_mask:0xf bank_mask:0xf bound_ctrl:1
	v_lshlrev_b32_e32 v23, 6, v20
	v_add_lshl_u32 v28, v23, v76, 2
	v_add_f32_dpp v16, v16, v16 row_mirror row_mask:0xf bank_mask:0xf bound_ctrl:1
	v_add_u32_e32 v23, s96, v28
	v_readlane_b32 s3, v16, 16
	v_readlane_b32 s6, v16, 48
	v_readlane_b32 s4, v16, 0
	v_readlane_b32 s5, v16, 32
	v_mov_b32_e32 v16, s3
	v_mov_b32_e32 v17, s6
	v_pk_add_f32 v[16:17], s[4:5], v[16:17]
	ds_read2_b32 v[18:19], v12 offset0:16 offset1:24
	v_add_f32_e32 v16, v16, v17
	v_fmac_f32_e32 v26, 0xbc800000, v16
	ds_read_b32 v29, v23
	ds_read_b32 v30, v21
	v_mul_f32_e32 v16, v26, v26
	v_add_f32_e32 v21, 1.0, v22
	v_rcp_f32_e32 v31, v21
	v_mov_b32_dpp v16, v16 quad_perm:[1,0,3,2] row_mask:0xf bank_mask:0xf bound_ctrl:1
	v_fmac_f32_e32 v16, v26, v26
	s_waitcnt lgkmcnt(1)
	v_add_f32_dpp v21, v29, v29 quad_perm:[1,0,3,2] row_mask:0xf bank_mask:0xf bound_ctrl:1
	v_lshlrev_b64 v[6:7], 10, v[6:7]
	v_add_f32_dpp v16, v16, v16 quad_perm:[2,3,0,1] row_mask:0xf bank_mask:0xf bound_ctrl:1
	v_add_f32_dpp v21, v21, v21 quad_perm:[2,3,0,1] row_mask:0xf bank_mask:0xf bound_ctrl:1
	v_lshl_add_u64 v[6:7], v[2:3], 0, v[6:7]
	v_add_f32_dpp v16, v16, v16 row_half_mirror row_mask:0xf bank_mask:0xf bound_ctrl:1
	v_add_f32_dpp v21, v21, v21 row_half_mirror row_mask:0xf bank_mask:0xf bound_ctrl:1
	s_nop 0
	v_add_f32_dpp v16, v16, v16 row_mirror row_mask:0xf bank_mask:0xf bound_ctrl:1
	v_add_f32_dpp v21, v21, v21 row_mirror row_mask:0xf bank_mask:0xf bound_ctrl:1
	v_readlane_b32 s3, v16, 16
	v_readlane_b32 s6, v16, 48
	v_readlane_b32 s4, v16, 0
	v_readlane_b32 s5, v16, 32
	v_mov_b32_e32 v16, s3
	v_mov_b32_e32 v17, s6
	v_readlane_b32 s3, v21, 16
	v_readlane_b32 s6, v21, 48
	v_pk_add_f32 v[16:17], s[4:5], v[16:17]
	v_readlane_b32 s4, v21, 0
	v_readlane_b32 s5, v21, 32
	v_mov_b32_e32 v22, s3
	v_mov_b32_e32 v23, s6
	v_pk_add_f32 v[22:23], s[4:5], v[22:23]
	v_mov_b32_e32 v25, v16
	v_add_f32_e32 v21, v22, v23
	v_fmac_f32_e32 v29, 0xbc800000, v21
	v_mul_f32_e32 v21, v29, v29
	s_nop 1
	v_mov_b32_dpp v21, v21 quad_perm:[1,0,3,2] row_mask:0xf bank_mask:0xf bound_ctrl:1
	v_fmac_f32_e32 v21, v29, v29
	s_nop 1
	v_add_f32_dpp v21, v21, v21 quad_perm:[2,3,0,1] row_mask:0xf bank_mask:0xf bound_ctrl:1
	s_nop 1
	v_add_f32_dpp v21, v21, v21 row_half_mirror row_mask:0xf bank_mask:0xf bound_ctrl:1
	s_nop 1
	v_add_f32_dpp v21, v21, v21 row_mirror row_mask:0xf bank_mask:0xf bound_ctrl:1
	s_nop 0
	v_readlane_b32 s3, v21, 16
	v_readlane_b32 s6, v21, 48
	v_readlane_b32 s4, v21, 0
	v_readlane_b32 s5, v21, 32
	v_mov_b32_e32 v22, s3
	v_mov_b32_e32 v23, s6
	v_pk_add_f32 v[22:23], s[4:5], v[22:23]
	s_nop 0
	v_mov_b32_e32 v24, v22
	v_mov_b32_e32 v16, v23
	v_pk_add_f32 v[16:17], v[24:25], v[16:17]
	s_nop 0
	v_pk_fma_f32 v[16:17], v[16:17], s[78:79], v[4:5] op_sel_hi:[1,0,0]
	s_nop 0
	v_mul_f32_e32 v21, 0x4b800000, v17
	v_cmp_gt_f32_e32 vcc, s91, v17
	s_nop 1
	v_cndmask_b32_e32 v17, v17, v21, vcc
	v_rsq_f32_e32 v17, v17
	v_ashrrev_i32_e32 v21, 31, v20
	v_lshl_add_u64 v[20:21], s[0:1], 0, v[20:21]
	v_mul_f32_e32 v22, 0x45800000, v17
	v_cndmask_b32_e32 v17, v17, v22, vcc
	v_mul_f32_e32 v17, v26, v17
	v_fma_f32 v17, v9, v17, v8
	s_waitcnt lgkmcnt(0)
	v_fmac_f32_e32 v17, v18, v30
	v_mul_f32_e32 v18, 0x4b800000, v16
	v_cmp_gt_f32_e32 vcc, s91, v16
	v_mul_f32_e32 v17, v17, v27
	v_mul_f32_e32 v17, v31, v17
	v_cndmask_b32_e32 v16, v16, v18, vcc
	v_rsq_f32_e32 v16, v16
	v_bfe_u32 v18, v17, 16, 1
	v_add3_u32 v17, v17, v18, s97
	global_store_short_d16_hi v[6:7], v17, off
	v_mul_f32_e32 v7, 0xbfb8aa3b, v15
	v_mul_f32_e32 v6, 0x45800000, v16
	v_exp_f32_e32 v7, v7
	v_cndmask_b32_e32 v6, v16, v6, vcc
	v_add_u32_e32 v16, s41, v28
	ds_read_b32 v16, v16
	v_add_f32_e32 v7, 1.0, v7
	v_mul_f32_e32 v6, v29, v6
	v_rcp_f32_e32 v7, v7
	v_fma_f32 v6, v9, v6, v8
	s_waitcnt lgkmcnt(0)
	v_fmac_f32_e32 v6, v19, v16
	v_mul_f32_e32 v6, v6, v15
	v_mul_f32_e32 v6, v7, v6
	v_add_u32_e32 v16, 32, v78
	v_bfe_u32 v7, v6, 16, 1
	v_lshlrev_b32_e32 v17, 6, v16
	v_add3_u32 v15, v6, v7, s97
	v_lshlrev_b64 v[6:7], 10, v[20:21]
	v_add_lshl_u32 v20, v17, v76, 2
	v_add_u32_e32 v17, s96, v20
	ds_read_b32 v26, v17
	v_lshl_add_u64 v[6:7], v[2:3], 0, v[6:7]
	global_store_short_d16_hi v[6:7], v15, off
	v_ashrrev_i32_e32 v17, 31, v16
	v_lshl_add_u64 v[6:7], s[0:1], 0, v[16:17]
	s_waitcnt lgkmcnt(0)
	v_add_f32_dpp v15, v26, v26 quad_perm:[1,0,3,2] row_mask:0xf bank_mask:0xf bound_ctrl:1
	ds_read2_b32 v[18:19], v12 offset0:32 offset1:40
	v_lshlrev_b64 v[6:7], 10, v[6:7]
	v_add_f32_dpp v15, v15, v15 quad_perm:[2,3,0,1] row_mask:0xf bank_mask:0xf bound_ctrl:1
	v_lshl_add_u64 v[6:7], v[2:3], 0, v[6:7]
	s_nop 0
	v_add_f32_dpp v15, v15, v15 row_half_mirror row_mask:0xf bank_mask:0xf bound_ctrl:1
	s_nop 1
	v_add_f32_dpp v15, v15, v15 row_mirror row_mask:0xf bank_mask:0xf bound_ctrl:1
	s_nop 0
	v_readlane_b32 s3, v15, 16
	v_readlane_b32 s6, v15, 48
	v_readlane_b32 s4, v15, 0
	v_readlane_b32 s5, v15, 32
	v_mov_b32_e32 v16, s3
	v_mov_b32_e32 v17, s6
	v_pk_add_f32 v[16:17], s[4:5], v[16:17]
	s_nop 0
	v_add_f32_e32 v15, v16, v17
	v_fmac_f32_e32 v26, 0xbc800000, v15
	v_mul_f32_e32 v15, v26, v26
	s_nop 1
	v_mov_b32_dpp v15, v15 quad_perm:[1,0,3,2] row_mask:0xf bank_mask:0xf bound_ctrl:1
	v_fmac_f32_e32 v15, v26, v26
	s_nop 1
	v_add_f32_dpp v15, v15, v15 quad_perm:[2,3,0,1] row_mask:0xf bank_mask:0xf bound_ctrl:1
	s_nop 1
	v_add_f32_dpp v15, v15, v15 row_half_mirror row_mask:0xf bank_mask:0xf bound_ctrl:1
	s_nop 1
	v_add_f32_dpp v15, v15, v15 row_mirror row_mask:0xf bank_mask:0xf bound_ctrl:1
	s_nop 0
	v_readlane_b32 s4, v15, 0
	v_readlane_b32 s3, v15, 16
	v_readlane_b32 s5, v15, 32
	v_readlane_b32 s6, v15, 48
	v_add_u32_e32 v15, s41, v20
	v_mul_f32_e32 v20, 0xbfb8aa3b, v14
	v_exp_f32_e32 v21, v20
	v_add_u32_e32 v20, 40, v78
	v_lshlrev_b32_e32 v22, 6, v20
	v_add_lshl_u32 v27, v22, v76, 2
	v_add_u32_e32 v22, s96, v27
	ds_read_b32 v28, v22
	ds_read_b32 v15, v15
	v_add_f32_e32 v21, 1.0, v21
	v_rcp_f32_e32 v29, v21
	v_mov_b32_e32 v16, s3
	s_waitcnt lgkmcnt(1)
	v_add_f32_dpp v21, v28, v28 quad_perm:[1,0,3,2] row_mask:0xf bank_mask:0xf bound_ctrl:1
	v_mov_b32_e32 v17, s6
	v_pk_add_f32 v[16:17], s[4:5], v[16:17]
	v_add_f32_dpp v21, v21, v21 quad_perm:[2,3,0,1] row_mask:0xf bank_mask:0xf bound_ctrl:1
	v_mov_b32_e32 v25, v16
	s_nop 0
	v_add_f32_dpp v21, v21, v21 row_half_mirror row_mask:0xf bank_mask:0xf bound_ctrl:1
	s_nop 1
	v_add_f32_dpp v21, v21, v21 row_mirror row_mask:0xf bank_mask:0xf bound_ctrl:1
	s_nop 0
	v_readlane_b32 s3, v21, 16
	v_readlane_b32 s6, v21, 48
	v_readlane_b32 s4, v21, 0
	v_readlane_b32 s5, v21, 32
	v_mov_b32_e32 v22, s3
	v_mov_b32_e32 v23, s6
	v_pk_add_f32 v[22:23], s[4:5], v[22:23]
	s_nop 0
	v_add_f32_e32 v21, v22, v23
	v_fmac_f32_e32 v28, 0xbc800000, v21
	v_mul_f32_e32 v21, v28, v28
	s_nop 1
	v_mov_b32_dpp v21, v21 quad_perm:[1,0,3,2] row_mask:0xf bank_mask:0xf bound_ctrl:1
	v_fmac_f32_e32 v21, v28, v28
	s_nop 1
	v_add_f32_dpp v21, v21, v21 quad_perm:[2,3,0,1] row_mask:0xf bank_mask:0xf bound_ctrl:1
	s_nop 1
	v_add_f32_dpp v21, v21, v21 row_half_mirror row_mask:0xf bank_mask:0xf bound_ctrl:1
	s_nop 1
	v_add_f32_dpp v21, v21, v21 row_mirror row_mask:0xf bank_mask:0xf bound_ctrl:1
	s_nop 0
	v_readlane_b32 s3, v21, 16
	v_readlane_b32 s6, v21, 48
	v_readlane_b32 s4, v21, 0
	v_readlane_b32 s5, v21, 32
	v_mov_b32_e32 v22, s3
	v_mov_b32_e32 v23, s6
	v_pk_add_f32 v[22:23], s[4:5], v[22:23]
	s_nop 0
	v_mov_b32_e32 v24, v22
	v_mov_b32_e32 v16, v23
	v_pk_add_f32 v[16:17], v[24:25], v[16:17]
	s_nop 0
	v_pk_fma_f32 v[16:17], v[16:17], s[78:79], v[4:5] op_sel_hi:[1,0,0]
	s_nop 0
	v_mul_f32_e32 v21, 0x4b800000, v17
	v_cmp_gt_f32_e32 vcc, s91, v17
	s_nop 1
	v_cndmask_b32_e32 v17, v17, v21, vcc
	v_rsq_f32_e32 v17, v17
	v_ashrrev_i32_e32 v21, 31, v20
	v_lshl_add_u64 v[20:21], s[0:1], 0, v[20:21]
	v_mul_f32_e32 v22, 0x45800000, v17
	v_cndmask_b32_e32 v17, v17, v22, vcc
	v_mul_f32_e32 v17, v26, v17
	v_fma_f32 v17, v9, v17, v8
	s_waitcnt lgkmcnt(0)
	v_fmac_f32_e32 v17, v18, v15
	v_mul_f32_e32 v14, v17, v14
	v_mul_f32_e32 v15, 0x4b800000, v16
	v_cmp_gt_f32_e32 vcc, s91, v16
	v_mul_f32_e32 v14, v29, v14
	s_nop 0
	v_cndmask_b32_e32 v15, v16, v15, vcc
	v_rsq_f32_e32 v15, v15
	v_bfe_u32 v16, v14, 16, 1
	v_add3_u32 v14, v14, v16, s97
	global_store_short_d16_hi v[6:7], v14, off
	v_add_u32_e32 v14, s41, v27
	v_mul_f32_e32 v7, 0xbfb8aa3b, v13
	ds_read_b32 v14, v14
	v_mul_f32_e32 v6, 0x45800000, v15
	v_exp_f32_e32 v7, v7
	v_cndmask_b32_e32 v6, v15, v6, vcc
	v_mul_f32_e32 v6, v28, v6
	v_fma_f32 v6, v9, v6, v8
	v_add_f32_e32 v7, 1.0, v7
	s_waitcnt lgkmcnt(0)
	v_fmac_f32_e32 v6, v19, v14
	v_add_u32_e32 v14, 48, v78
	v_rcp_f32_e32 v7, v7
	v_lshlrev_b32_e32 v15, 6, v14
	v_add_lshl_u32 v16, v15, v76, 2
	v_add_u32_e32 v15, s96, v16
	v_mul_f32_e32 v6, v6, v13
	ds_read_b32 v22, v15
	v_mul_f32_e32 v6, v7, v6
	v_bfe_u32 v7, v6, 16, 1
	v_add3_u32 v13, v6, v7, s97
	v_lshlrev_b64 v[6:7], 10, v[20:21]
	v_lshl_add_u64 v[6:7], v[2:3], 0, v[6:7]
	global_store_short_d16_hi v[6:7], v13, off
	s_waitcnt lgkmcnt(0)
	v_add_f32_dpp v13, v22, v22 quad_perm:[1,0,3,2] row_mask:0xf bank_mask:0xf bound_ctrl:1
	v_ashrrev_i32_e32 v15, 31, v14
	v_lshl_add_u64 v[6:7], s[0:1], 0, v[14:15]
	v_add_f32_dpp v13, v13, v13 quad_perm:[2,3,0,1] row_mask:0xf bank_mask:0xf bound_ctrl:1
	v_add_u32_e32 v17, s41, v16
	v_mul_f32_e32 v16, 0xbfb8aa3b, v11
	v_add_f32_dpp v13, v13, v13 row_half_mirror row_mask:0xf bank_mask:0xf bound_ctrl:1
	v_exp_f32_e32 v18, v16
	v_add_u32_e32 v16, 56, v78
	v_add_f32_dpp v13, v13, v13 row_mirror row_mask:0xf bank_mask:0xf bound_ctrl:1
	v_lshlrev_b32_e32 v19, 6, v16
	v_readlane_b32 s3, v13, 16
	v_readlane_b32 s6, v13, 48
	v_readlane_b32 s4, v13, 0
	v_readlane_b32 s5, v13, 32
	v_mov_b32_e32 v14, s3
	v_mov_b32_e32 v15, s6
	v_pk_add_f32 v[14:15], s[4:5], v[14:15]
	v_add_lshl_u32 v23, v19, v76, 2
	v_add_f32_e32 v13, v14, v15
	v_fmac_f32_e32 v22, 0xbc800000, v13
	v_mul_f32_e32 v13, v22, v22
	v_add_u32_e32 v19, s96, v23
	v_lshlrev_b64 v[6:7], 10, v[6:7]
	v_mov_b32_dpp v13, v13 quad_perm:[1,0,3,2] row_mask:0xf bank_mask:0xf bound_ctrl:1
	v_fmac_f32_e32 v13, v22, v22
	v_lshl_add_u64 v[6:7], v[2:3], 0, v[6:7]
	s_nop 0
	v_add_f32_dpp v13, v13, v13 quad_perm:[2,3,0,1] row_mask:0xf bank_mask:0xf bound_ctrl:1
	s_nop 1
	v_add_f32_dpp v13, v13, v13 row_half_mirror row_mask:0xf bank_mask:0xf bound_ctrl:1
	s_nop 1
	v_add_f32_dpp v13, v13, v13 row_mirror row_mask:0xf bank_mask:0xf bound_ctrl:1
	s_nop 0
	v_readlane_b32 s4, v13, 0
	v_readlane_b32 s3, v13, 16
	v_readlane_b32 s5, v13, 32
	v_readlane_b32 s6, v13, 48
	ds_read2_b32 v[12:13], v12 offset0:48 offset1:56
	ds_read_b32 v24, v19
	ds_read_b32 v25, v17
	v_add_f32_e32 v17, 1.0, v18
	v_rcp_f32_e32 v26, v17
	v_mov_b32_e32 v14, s3
	s_waitcnt lgkmcnt(1)
	v_add_f32_dpp v17, v24, v24 quad_perm:[1,0,3,2] row_mask:0xf bank_mask:0xf bound_ctrl:1
	v_mov_b32_e32 v15, s6
	v_pk_add_f32 v[14:15], s[4:5], v[14:15]
	v_add_f32_dpp v17, v17, v17 quad_perm:[2,3,0,1] row_mask:0xf bank_mask:0xf bound_ctrl:1
	v_mov_b32_e32 v21, v14
	s_nop 0
	v_add_f32_dpp v17, v17, v17 row_half_mirror row_mask:0xf bank_mask:0xf bound_ctrl:1
	s_nop 1
	v_add_f32_dpp v17, v17, v17 row_mirror row_mask:0xf bank_mask:0xf bound_ctrl:1
	s_nop 0
	v_readlane_b32 s3, v17, 16
	v_readlane_b32 s6, v17, 48
	v_readlane_b32 s4, v17, 0
	v_readlane_b32 s5, v17, 32
	v_mov_b32_e32 v18, s3
	v_mov_b32_e32 v19, s6
	v_pk_add_f32 v[18:19], s[4:5], v[18:19]
	s_nop 0
	v_add_f32_e32 v17, v18, v19
	v_fmac_f32_e32 v24, 0xbc800000, v17
	v_mul_f32_e32 v17, v24, v24
	s_nop 1
	v_mov_b32_dpp v17, v17 quad_perm:[1,0,3,2] row_mask:0xf bank_mask:0xf bound_ctrl:1
	v_fmac_f32_e32 v17, v24, v24
	s_nop 1
	v_add_f32_dpp v17, v17, v17 quad_perm:[2,3,0,1] row_mask:0xf bank_mask:0xf bound_ctrl:1
	s_nop 1
	v_add_f32_dpp v17, v17, v17 row_half_mirror row_mask:0xf bank_mask:0xf bound_ctrl:1
	s_nop 1
	v_add_f32_dpp v17, v17, v17 row_mirror row_mask:0xf bank_mask:0xf bound_ctrl:1
	s_nop 0
	v_readlane_b32 s3, v17, 16
	v_readlane_b32 s6, v17, 48
	v_readlane_b32 s4, v17, 0
	v_readlane_b32 s5, v17, 32
	v_mov_b32_e32 v18, s3
	v_mov_b32_e32 v19, s6
	v_pk_add_f32 v[18:19], s[4:5], v[18:19]
	v_ashrrev_i32_e32 v17, 31, v16
	v_mov_b32_e32 v20, v18
	v_mov_b32_e32 v14, v19
	v_pk_add_f32 v[14:15], v[20:21], v[14:15]
	s_nop 0
	v_pk_fma_f32 v[4:5], v[14:15], s[78:79], v[4:5] op_sel_hi:[1,0,0]
	s_nop 0
	v_mul_f32_e32 v14, 0x4b800000, v5
	v_cmp_gt_f32_e32 vcc, s91, v5
	s_nop 1
	v_cndmask_b32_e32 v5, v5, v14, vcc
	v_rsq_f32_e32 v5, v5
	v_lshl_add_u64 v[14:15], s[0:1], 0, v[16:17]
	v_mul_f32_e32 v16, 0x45800000, v5
	v_cndmask_b32_e32 v5, v5, v16, vcc
	v_mul_f32_e32 v5, v22, v5
	v_fma_f32 v5, v9, v5, v8
	s_waitcnt lgkmcnt(0)
	v_fmac_f32_e32 v5, v12, v25
	v_mul_f32_e32 v5, v5, v11
	v_mul_f32_e32 v11, 0x4b800000, v4
	v_cmp_gt_f32_e32 vcc, s91, v4
	v_mul_f32_e32 v5, v26, v5
	s_nop 0
	v_cndmask_b32_e32 v4, v4, v11, vcc
	v_rsq_f32_e32 v4, v4
	v_bfe_u32 v11, v5, 16, 1
	v_add3_u32 v5, v5, v11, s97
	global_store_short_d16_hi v[6:7], v5, off
	v_mul_f32_e32 v5, 0x45800000, v4
	v_cndmask_b32_e32 v4, v4, v5, vcc
	v_mul_f32_e32 v5, 0xbfb8aa3b, v10
	v_exp_f32_e32 v5, v5
	v_add_u32_e32 v6, s41, v23
	ds_read_b32 v6, v6
	v_mul_f32_e32 v4, v24, v4
	v_add_f32_e32 v5, 1.0, v5
	v_rcp_f32_e32 v5, v5
	v_fmac_f32_e32 v8, v9, v4
	s_waitcnt lgkmcnt(0)
	v_fmac_f32_e32 v8, v13, v6
	v_mul_f32_e32 v4, v8, v10
	v_mul_f32_e32 v4, v5, v4
	v_bfe_u32 v5, v4, 16, 1
	v_add3_u32 v6, v4, v5, s97
	v_lshlrev_b64 v[4:5], 10, v[14:15]
	v_lshl_add_u64 v[2:3], v[2:3], 0, v[4:5]
	global_store_short_d16_hi v[2:3], v6, off
	s_cbranch_scc0 .LBB0_564
	s_branch .LBB0_532
